# speedup vs baseline: 1.0578x; 1.0029x over previous
.LBB0_481:
	s_cmp_gt_i32 s34, 3
	s_cselect_b64 s[0:1], -1, 0
	s_cmp_lt_i32 s35, 3
	s_cselect_b64 s[4:5], -1, 0
	s_or_b64 s[0:1], s[0:1], s[4:5]
	s_and_b64 vcc, exec, s[0:1]
	s_cbranch_vccnz .LBB0_536
	v_and_b32_e32 v1, 0x3ff, v0
	s_mov_b64 s[0:1], 0
	v_mov_b32_e32 v3, v1
	s_load_dword s3, s[92:93], 0xd8
	v_ashrrev_i32_e32 v107, 6, v3
	v_and_b32_e32 v102, 15, v3
	v_bfe_u32 v6, v3, 4, 2
	v_and_b32_e32 v10, 48, v3
	s_waitcnt lgkmcnt(0)
	s_and_b32 s0, s3, 7
	s_cmp_lg_u32 s0, 0
	s_cselect_b64 s[4:5], -1, 0
	s_cmp_lt_i32 s3, 8
	s_cselect_b64 s[6:7], -1, 0
	s_lshl_b32 s0, s2, 5
	s_and_b32 s61, s0, 0xe0
	s_movk_i32 s0, 0x4300
	v_mul_lo_u32 v2, v107, s0
	v_add_u32_e32 v5, 0, v2
	v_and_b32_e32 v2, 63, v3
	v_lshrrev_b32_e32 v3, 1, v3
	v_lshlrev_b32_e32 v4, 3, v6
	v_mov_b32_e32 v105, 0
	v_mul_u32_u24_e32 v7, 0x210, v102
	s_movk_i32 s0, 0x110
	v_and_b32_e32 v104, 24, v3
	s_or_b64 s[36:37], s[6:7], s[4:5]
	v_lshlrev_b32_e32 v106, 2, v6
	v_and_b32_e32 v6, 8, v4
	v_lshrrev_b32_e32 v200, 1, v102
	v_mul_u32_u24_e32 v200, 0x410, v200
	v_and_b32_e32 v201, 1, v102
	v_lshlrev_b32_e32 v201, 3, v201
	v_lshl_add_u32 v201, v10, 1, v201
	v_add3_u32 v137, v5, v200, v201
	v_mad_u32_u24 v7, v102, s0, v5
	v_lshlrev_b32_e32 v11, 3, v2
	v_lshlrev_b32_e32 v12, 2, v2
	v_lshl_add_u64 v[8:9], s[86:87], 0, v[104:105]
	s_mov_b64 s[4:5], 0x4c00200
	s_mov_b32 s1, 0
	s_lshr_b32 s33, s3, 3
	s_ashr_i32 s60, s2, 3
	v_lshlrev_b32_e32 v136, 6, v102
	v_mov_b32_e32 v103, v105
	v_lshl_add_u64 v[108:109], v[8:9], 0, s[4:5]
	s_mov_b32 s62, 0x2ac0000
	s_mov_b32 s63, 0x2ac4000
	v_lshlrev_b32_e32 v110, 1, v4
	s_mov_b64 s[38:39], 0x2a00000
	s_mov_b32 s64, 0x2a01000
	s_mov_b64 s[40:41], 0x2a80000
	s_mov_b32 s65, 0x2a80000
	s_mov_b32 s66, 0x2ac8000
	s_mov_b32 s67, 0x2acc000
	s_mov_b64 s[44:45], 0x4c00000
	v_lshlrev_b32_e32 v112, 1, v6
	s_mov_b64 s[46:47], 0x400
	v_lshlrev_b32_e32 v104, 2, v2
	v_add_u32_e32 v138, v7, v10
	v_lshl_add_u32 v139, v2, 4, v5
	v_mov_b32_e32 v202, 0x3dd2d3e8
	v_mov_b32_e32 v203, 0x3dd2d3e8
	v_mov_b32_e32 v204, 0x40135761
	v_mov_b32_e32 v205, 0x40135761
	v_add_u32_e32 v140, v5, v12
	s_mov_b32 s68, 0
	s_branch .LBB0_484

.LBB0_490:
	s_waitcnt vmcnt(3)
	v_mfma_f32_16x16x32_bf16 v[90:93], v[18:21], v[54:57], 0
	v_add_u32_e32 v111, 0x800, v139
	v_add_u32_e32 v113, 0x1000, v139
	v_add_u32_e32 v119, 0x1800, v139
	v_mfma_f32_16x16x32_bf16 v[94:97], v[6:9], v[54:57], 0
	ds_read_b128 v[82:85], v138 offset:12800
	ds_read_b128 v[78:81], v138 offset:12864
	ds_read_b128 v[74:77], v138 offset:12928
	ds_read_b128 v[70:73], v138 offset:12992
	ds_read_b128 v[98:101], v139
	ds_read_b128 v[144:147], v139 offset:1040
	ds_read_b128 v[152:155], v139 offset:2080
	ds_read_b128 v[156:159], v139 offset:3120
	v_mfma_f32_16x16x32_bf16 v[148:151], v[10:13], v[54:57], 0
	ds_read_b128 v[164:167], v139 offset:4160
	ds_read_b128 v[168:171], v139 offset:5200
	ds_read_b128 v[86:89], v139 offset:6240
	ds_read_b128 v[66:69], v139 offset:7280
	ds_write2_b64 v137, v[90:91], v[92:93] offset1:2
	v_mfma_f32_16x16x32_bf16 v[160:163], v[14:17], v[54:57], 0
	ds_write2_b64 v137, v[94:95], v[96:97] offset0:16 offset1:18
	s_nop 0
	ds_write2_b64 v137, v[148:149], v[150:151] offset0:32 offset1:34
	s_nop 4
	ds_write2_b64 v137, v[160:161], v[162:163] offset0:48 offset1:50
	s_min_u32 s0, s6, 28
	v_mfma_f32_16x16x32_bf16 v[172:175], v[22:25], v[54:57], 0
	s_lshl_b32 s0, s0, 9
	s_waitcnt lgkmcnt(11)
	v_fma_f32 v62, -v142, v65, v98
	v_fma_f32 v64, v142, v63, v99
	v_mfma_f32_16x16x32_bf16 v[90:93], v[26:29], v[54:57], 0
	s_cmp_eq_u32 s6, 0
	v_mfma_f32_16x16x32_bf16 v[94:97], v[30:33], v[54:57], 0
	s_nop 0
	ds_write2_b64 v137, v[172:173], v[174:175] offset0:64 offset1:66
	s_nop 3
	ds_write2_b64 v137, v[90:91], v[92:93] offset0:80 offset1:82
	s_nop 0
	ds_write2_b64 v137, v[94:95], v[96:97] offset0:96 offset1:98
	v_fmac_f32_e32 v62, v141, v63
	v_mfma_f32_16x16x32_bf16 v[54:57], v[34:37], v[54:57], 0
	v_fmac_f32_e32 v64, v141, v65
	v_add_u32_e32 v65, 0x2000, v140
	v_fma_f32 v63, -v142, v64, v100
	s_nop 4
	ds_write2_b64 v137, v[54:55], v[56:57] offset0:112 offset1:114
	v_lshl_add_u64 v[54:55], v[116:117], 0, s[0:1]
	global_load_dwordx4 v[54:57], v[54:55], off offset:1536
	v_fmac_f32_e32 v101, v142, v62
	s_nop 0
	v_fmac_f32_e32 v63, v141, v62
	v_fmac_f32_e32 v101, v141, v64
	v_cvt_pk_bf16_f32 v62, v62, v64
	v_cvt_pk_bf16_f32 v64, v63, v101
	ds_write2_b32 v65, v62, v64 offset0:64 offset1:132
	s_waitcnt lgkmcnt(14)
	v_fma_f32 v62, -v142, v101, v144
	v_fma_f32 v64, v142, v63, v145
	v_add_u32_e32 v65, 0x2200, v140
	v_fmac_f32_e32 v62, v141, v63
	v_fmac_f32_e32 v64, v141, v101
	s_nop 0
	v_fma_f32 v63, -v142, v64, v146
	v_fmac_f32_e32 v147, v142, v62
	s_nop 0
	v_fmac_f32_e32 v63, v141, v62
	v_fmac_f32_e32 v147, v141, v64
	v_cvt_pk_bf16_f32 v62, v62, v64
	v_cvt_pk_bf16_f32 v64, v63, v147
	ds_write2_b32 v65, v62, v64 offset0:72 offset1:140
	v_fma_f32 v62, -v142, v147, v152
	v_fma_f32 v64, v142, v63, v153
	v_add_u32_e32 v65, 0x2400, v140
	v_fmac_f32_e32 v62, v141, v63
	v_fmac_f32_e32 v64, v141, v147
	s_nop 0
	v_fma_f32 v63, -v142, v64, v154
	v_fmac_f32_e32 v155, v142, v62
	s_nop 0
	v_fmac_f32_e32 v63, v141, v62
	v_fmac_f32_e32 v155, v141, v64
	v_cvt_pk_bf16_f32 v62, v62, v64
	v_cvt_pk_bf16_f32 v64, v63, v155
	ds_write2_b32 v65, v62, v64 offset0:80 offset1:148
	s_waitcnt lgkmcnt(14)
	v_fma_f32 v62, -v142, v155, v156
	v_fma_f32 v64, v142, v63, v157
	v_add_u32_e32 v65, 0x2600, v140
	v_fmac_f32_e32 v62, v141, v63
	v_fmac_f32_e32 v64, v141, v155
	s_nop 0
	v_fma_f32 v63, -v142, v64, v158
	v_fmac_f32_e32 v159, v142, v62
	s_nop 0
	v_fmac_f32_e32 v63, v141, v62
	v_fmac_f32_e32 v159, v141, v64
	v_cvt_pk_bf16_f32 v62, v62, v64
	v_cvt_pk_bf16_f32 v64, v63, v159
	ds_write2_b32 v65, v62, v64 offset0:88 offset1:156
	v_fma_f32 v62, -v142, v159, v164
	v_fma_f32 v64, v142, v63, v165
	v_add_u32_e32 v65, 0x2800, v140
	v_fmac_f32_e32 v62, v141, v63
	v_fmac_f32_e32 v64, v141, v159
	s_nop 0
	v_fma_f32 v63, -v142, v64, v166
	v_fmac_f32_e32 v167, v142, v62
	s_nop 0
	v_fmac_f32_e32 v63, v141, v62
	v_fmac_f32_e32 v167, v141, v64
	v_cvt_pk_bf16_f32 v62, v62, v64
	v_cvt_pk_bf16_f32 v64, v63, v167
	ds_write2_b32 v65, v62, v64 offset0:96 offset1:164
	s_waitcnt lgkmcnt(14)
	v_fma_f32 v62, -v142, v167, v168
	v_fma_f32 v64, v142, v63, v169
	v_add_u32_e32 v65, 0x2a00, v140
	v_fmac_f32_e32 v62, v141, v63
	v_fmac_f32_e32 v64, v141, v167
	s_nop 0
	v_fma_f32 v63, -v142, v64, v170
	v_fmac_f32_e32 v171, v142, v62
	s_nop 0
	v_fmac_f32_e32 v63, v141, v62
	v_fmac_f32_e32 v171, v141, v64
	v_cvt_pk_bf16_f32 v62, v62, v64
	v_cvt_pk_bf16_f32 v64, v63, v171
	ds_write2_b32 v65, v62, v64 offset0:104 offset1:172
	v_fma_f32 v62, -v142, v171, v86
	v_fma_f32 v64, v142, v63, v87
	v_add_u32_e32 v65, 0x2c00, v140
	v_fmac_f32_e32 v62, v141, v63
	v_fmac_f32_e32 v64, v141, v171
	s_nop 0
	v_fmac_f32_e32 v89, v142, v62
	v_fma_f32 v63, -v142, v64, v88
	s_nop 0
	v_fmac_f32_e32 v89, v141, v64
	v_fmac_f32_e32 v63, v141, v62
	v_cvt_pk_bf16_f32 v62, v62, v64
	s_waitcnt lgkmcnt(14)
	v_fma_f32 v86, -v142, v89, v66
	v_cvt_pk_bf16_f32 v64, v63, v89
	ds_write2_b32 v65, v62, v64 offset0:112 offset1:180
	v_fma_f32 v67, v142, v63, v67
	v_fmac_f32_e32 v86, v141, v63
	v_mfma_f32_16x16x32_bf16 v[62:65], v[50:53], v[82:85], 0
	v_mfma_f32_16x16x32_bf16 v[62:65], v[46:49], v[78:81], v[62:65]
	v_fmac_f32_e32 v67, v141, v89
	v_fmac_f32_e32 v69, v142, v86
	v_mfma_f32_16x16x32_bf16 v[62:65], v[42:45], v[74:77], v[62:65]
	v_fma_f32 v66, -v142, v67, v68
	v_mfma_f32_16x16x32_bf16 v[62:65], v[38:41], v[70:73], v[62:65]
	v_fmac_f32_e32 v66, v141, v86
	v_fmac_f32_e32 v69, v141, v67
	v_cvt_pk_bf16_f32 v67, v86, v67
	v_cvt_pk_bf16_f32 v68, v66, v69
	v_add_u32_e32 v74, 0x2e00, v140
	ds_write2_b32 v74, v67, v68 offset0:120 offset1:188
	s_cbranch_scc1 .LBB0_492
	s_waitcnt vmcnt(3)
	v_lshlrev_b32_e32 v70, 16, v124
	v_and_b32_e32 v71, 0xffff0000, v124
	v_pk_fma_f32 v[62:63], v[2:3], v[70:71], v[62:63]
	v_lshlrev_b32_e32 v72, 16, v125
	v_and_b32_e32 v73, 0xffff0000, v125
	v_pk_fma_f32 v[64:65], v[4:5], v[72:73], v[64:65]
	v_pk_mul_f32 v[70:71], v[62:63], v[62:63]
	v_pk_mul_f32 v[72:73], v[64:65], v[64:65]
	v_pk_fma_f32 v[70:71], v[70:71], v[202:203], v[204:205]
	v_pk_fma_f32 v[72:73], v[72:73], v[202:203], v[204:205]
	v_pk_mul_f32 v[70:71], v[70:71], v[62:63]
	v_pk_mul_f32 v[72:73], v[72:73], v[64:65]
	v_exp_f32_e64 v70, -v70
	v_exp_f32_e64 v71, -v71
	v_exp_f32_e64 v72, -v72
	v_exp_f32_e64 v73, -v73
	s_add_i32 s0, s6, -1
	v_pk_add_f32 v[70:71], v[70:71], 1.0 op_sel_hi:[1,0]
	v_pk_add_f32 v[72:73], v[72:73], 1.0 op_sel_hi:[1,0]
	v_rcp_f32_e32 v70, v70
	v_rcp_f32_e32 v71, v71
	v_rcp_f32_e32 v72, v72
	v_rcp_f32_e32 v73, v73
	s_lshl_b64 s[8:9], s[0:1], 15
	v_pk_mul_f32 v[62:63], v[62:63], v[70:71]
	v_pk_mul_f32 v[64:65], v[64:65], v[72:73]
	v_cvt_pk_bf16_f32 v62, v62, v63
	v_cvt_pk_bf16_f32 v63, v64, v65
	v_lshl_add_u64 v[64:65], v[130:131], 0, s[8:9]
	global_store_dwordx2 v[64:65], v[62:63], off
	global_load_dwordx2 v[124:125], v[132:133], off
.LBB0_492:
	s_waitcnt lgkmcnt(0)
	ds_read_b128 v[98:101], v138 offset:8448
	ds_read_b128 v[94:97], v138 offset:8512
	ds_read_b128 v[90:93], v138 offset:8576
	ds_read_b128 v[86:89], v138 offset:8640
	ds_read_b128 v[156:159], v139
	ds_read_b128 v[160:163], v139 offset:1040
	ds_read_b128 v[164:167], v139 offset:2080
	s_waitcnt vmcnt(1)
	v_mfma_f32_16x16x32_bf16 v[144:147], v[18:21], v[58:61], 0
	ds_read_b128 v[82:85], v139 offset:3120
	ds_read_b128 v[78:81], v139 offset:4160
	ds_read_b128 v[74:77], v139 offset:5200
	s_waitcnt lgkmcnt(5)
	v_fma_f32 v67, -v142, v69, v156
	v_fma_f32 v68, v142, v66, v157
	v_mfma_f32_16x16x32_bf16 v[148:151], v[6:9], v[58:61], 0
	ds_read_b128 v[70:73], v139 offset:6240
	ds_read_b128 v[62:65], v139 offset:7280
	v_mfma_f32_16x16x32_bf16 v[152:155], v[10:13], v[58:61], 0
	v_fmac_f32_e32 v67, v141, v66
	v_fmac_f32_e32 v68, v141, v69
	ds_write2_b64 v137, v[144:145], v[146:147] offset1:2
	v_mfma_f32_16x16x32_bf16 v[168:171], v[14:17], v[58:61], 0
	s_nop 0
	ds_write2_b64 v137, v[148:149], v[150:151] offset0:16 offset1:18
	s_nop 1
	ds_write2_b64 v137, v[152:153], v[154:155] offset0:32 offset1:34
	s_nop 2
	ds_write2_b64 v137, v[168:169], v[170:171] offset0:48 offset1:50
	v_mfma_f32_16x16x32_bf16 v[172:175], v[22:25], v[58:61], 0
	v_fmac_f32_e32 v159, v142, v67
	v_fma_f32 v66, -v142, v68, v158
	v_mfma_f32_16x16x32_bf16 v[144:147], v[26:29], v[58:61], 0
	v_add_u32_e32 v69, 0x3000, v140
	v_mfma_f32_16x16x32_bf16 v[148:151], v[30:33], v[58:61], 0
	v_fmac_f32_e32 v66, v141, v67
	v_fmac_f32_e32 v159, v141, v68
	v_mfma_f32_16x16x32_bf16 v[58:61], v[34:37], v[58:61], 0
	v_cvt_pk_bf16_f32 v67, v67, v68
	v_cvt_pk_bf16_f32 v68, v66, v159
	ds_write2_b64 v137, v[172:173], v[174:175] offset0:64 offset1:66
	ds_write2_b64 v137, v[144:145], v[146:147] offset0:80 offset1:82
	s_nop 0
	ds_write2_b64 v137, v[148:149], v[150:151] offset0:96 offset1:98
	s_nop 1
	ds_write2_b64 v137, v[58:59], v[60:61] offset0:112 offset1:114
	ds_write2_b32 v69, v67, v68 offset0:128 offset1:196
	s_waitcnt lgkmcnt(14)
	v_fma_f32 v67, -v142, v159, v160
	v_fma_f32 v68, v142, v66, v161
	v_add_u32_e32 v69, 0x3400, v140
	v_fmac_f32_e32 v67, v141, v66
	v_fmac_f32_e32 v68, v141, v159
	s_add_i32 s7, s6, 1
	v_fma_f32 v66, -v142, v68, v162
	v_fmac_f32_e32 v163, v142, v67
	s_min_u32 s0, s7, 28
	v_fmac_f32_e32 v66, v141, v67
	v_fmac_f32_e32 v163, v141, v68
	v_cvt_pk_bf16_f32 v67, v67, v68
	v_cvt_pk_bf16_f32 v68, v66, v163
	ds_write2_b32 v69, v67, v68 offset0:8 offset1:76
	v_fma_f32 v67, -v142, v163, v164
	v_fma_f32 v68, v142, v66, v165
	s_lshl_b32 s0, s0, 9
	v_fmac_f32_e32 v67, v141, v66
	v_fmac_f32_e32 v68, v141, v163
	v_lshl_add_u64 v[58:59], v[116:117], 0, s[0:1]
	v_fmac_f32_e32 v167, v142, v67
	v_fma_f32 v66, -v142, v68, v166
	s_min_u32 s0, s7, 30
	v_fmac_f32_e32 v167, v141, v68
	v_fmac_f32_e32 v66, v141, v67
	v_cvt_pk_bf16_f32 v67, v67, v68
	s_waitcnt lgkmcnt(14)
	v_fma_f32 v82, -v142, v167, v82
	v_cvt_pk_bf16_f32 v68, v66, v167
	ds_write2_b32 v69, v67, v68 offset0:144 offset1:212
	v_fma_f32 v83, v142, v66, v83
	v_fmac_f32_e32 v82, v141, v66
	v_mfma_f32_16x16x32_bf16 v[66:69], v[50:53], v[98:101], 0
	s_lshl_b32 s0, s0, 9
	v_mfma_f32_16x16x32_bf16 v[66:69], v[46:49], v[94:97], v[66:69]
	v_fmac_f32_e32 v83, v141, v167
	v_fmac_f32_e32 v85, v142, v82
	v_mfma_f32_16x16x32_bf16 v[66:69], v[42:45], v[90:93], v[66:69]
	v_fma_f32 v84, -v142, v83, v84
	v_mfma_f32_16x16x32_bf16 v[66:69], v[38:41], v[86:89], v[66:69]
	v_fmac_f32_e32 v84, v141, v82
	v_fmac_f32_e32 v85, v141, v83
	v_cvt_pk_bf16_f32 v82, v82, v83
	v_cvt_pk_bf16_f32 v83, v84, v85
	v_add_u32_e32 v94, 0x3800, v140
	ds_write2_b32 v94, v82, v83 offset0:24 offset1:92
	v_lshlrev_b32_e32 v82, 16, v126
	v_and_b32_e32 v83, 0xffff0000, v126
	v_pk_fma_f32 v[66:67], v[2:3], v[82:83], v[66:67]
	v_lshlrev_b32_e32 v86, 16, v127
	v_and_b32_e32 v87, 0xffff0000, v127
	v_pk_fma_f32 v[68:69], v[4:5], v[86:87], v[68:69]
	v_pk_mul_f32 v[82:83], v[66:67], v[66:67]
	v_pk_mul_f32 v[86:87], v[68:69], v[68:69]
	v_pk_fma_f32 v[82:83], v[82:83], v[202:203], v[204:205]
	v_pk_fma_f32 v[86:87], v[86:87], v[202:203], v[204:205]
	v_pk_mul_f32 v[82:83], v[82:83], v[66:67]
	v_pk_mul_f32 v[86:87], v[86:87], v[68:69]
	v_exp_f32_e64 v82, -v82
	v_exp_f32_e64 v83, -v83
	v_exp_f32_e64 v86, -v86
	v_exp_f32_e64 v87, -v87
	s_waitcnt lgkmcnt(14)
	v_pk_add_f32 v[82:83], v[82:83], 1.0 op_sel_hi:[1,0]
	v_pk_add_f32 v[86:87], v[86:87], 1.0 op_sel_hi:[1,0]
	v_rcp_f32_e32 v82, v82
	v_rcp_f32_e32 v83, v83
	v_rcp_f32_e32 v86, v86
	v_rcp_f32_e32 v87, v87
	v_fma_f32 v95, -v142, v85, v78
	v_fma_f32 v90, v142, v84, v79
	v_or_b32_e32 v79, v115, v135
	v_or_b32_e32 v78, v114, v134
	v_pk_mul_f32 v[66:67], v[66:67], v[82:83]
	v_pk_mul_f32 v[68:69], v[68:69], v[86:87]
	v_cvt_pk_bf16_f32 v66, v66, v67
	v_cvt_pk_bf16_f32 v67, v68, v69
	v_lshlrev_b64 v[68:69], 11, v[78:79]
	v_lshl_add_u64 v[68:69], v[128:129], 0, v[68:69]
	global_load_dwordx4 v[58:61], v[58:59], off offset:1536
	global_store_dwordx2 v[68:69], v[66:67], off
	v_lshl_add_u64 v[66:67], v[122:123], 0, s[0:1]
	global_load_dwordx2 v[126:127], v[66:67], off offset:512
	v_fmac_f32_e32 v95, v141, v84
	v_fmac_f32_e32 v90, v141, v85
	v_add_u32_e32 v69, 0x3c00, v140
	v_fma_f32 v66, -v142, v90, v80
	v_fmac_f32_e32 v81, v142, v95
	v_cvt_pk_bf16_f32 v67, v95, v90
	v_fmac_f32_e32 v66, v141, v95
	v_fmac_f32_e32 v81, v141, v90
	s_add_i32 s0, s6, 2
	v_cvt_pk_bf16_f32 v68, v66, v81
	ds_write2_b32 v94, v67, v68 offset0:160 offset1:228
	v_fma_f32 v67, -v142, v81, v74
	v_fma_f32 v68, v142, v66, v75
	v_lshl_add_u64 v[132:133], v[132:133], 0, s[46:47]
	v_fmac_f32_e32 v67, v141, v66
	v_fmac_f32_e32 v68, v141, v81
	s_cmp_lt_u32 s6, 30
	v_fma_f32 v66, -v142, v68, v76
	v_fmac_f32_e32 v77, v142, v67
	v_lshl_add_u64 v[134:135], v[134:135], 0, 32
	v_fmac_f32_e32 v66, v141, v67
	v_fmac_f32_e32 v77, v141, v68
	v_cvt_pk_bf16_f32 v67, v67, v68
	v_cvt_pk_bf16_f32 v68, v66, v77
	ds_write2_b32 v69, v67, v68 offset0:40 offset1:108
	s_waitcnt lgkmcnt(14)
	v_fma_f32 v67, -v142, v77, v70
	v_fma_f32 v68, v142, v66, v71
	s_nop 0
	v_fmac_f32_e32 v67, v141, v66
	v_fmac_f32_e32 v68, v141, v77
	s_nop 0
	v_fma_f32 v66, -v142, v68, v72
	v_fmac_f32_e32 v73, v142, v67
	s_nop 0
	v_fmac_f32_e32 v66, v141, v67
	v_fmac_f32_e32 v73, v141, v68
	v_cvt_pk_bf16_f32 v67, v67, v68
	v_cvt_pk_bf16_f32 v68, v66, v73
	ds_write2_b32 v69, v67, v68 offset0:176 offset1:244
	v_fma_f32 v62, -v142, v73, v62
	v_fma_f32 v67, v142, v66, v63
	s_nop 0
	v_fmac_f32_e32 v62, v141, v66
	v_fmac_f32_e32 v67, v141, v73
	v_add_u32_e32 v66, 0x4000, v140
	v_fma_f32 v63, -v142, v67, v64
	v_fmac_f32_e32 v65, v142, v62
	s_nop 0
	v_fmac_f32_e32 v63, v141, v62
	v_fmac_f32_e32 v65, v141, v67
	v_cvt_pk_bf16_f32 v62, v62, v67
	v_cvt_pk_bf16_f32 v64, v63, v65
	ds_write2_b32 v66, v62, v64 offset0:56 offset1:124
	s_waitcnt lgkmcnt(0)
	s_cbranch_scc0 .LBB0_483
	s_mov_b32 s6, s0
	s_branch .LBB0_490

.LBB0_1011:
	s_add_i32 s0, s49, s50
	s_lshl_b32 s27, s54, 14
	v_cmp_eq_u32_e32 vcc, 0, v56
	v_mov_b32_e32 v56, 1
	s_and_saveexec_b64 s[28:29], vcc
	s_cbranch_execz .LBB0_1019
	s_add_i32 s30, s0, 64
	v_cmp_le_i32_e32 vcc, s30, v48
	v_mov_b32_e32 v56, 0
	s_and_saveexec_b64 s[30:31], vcc
	s_cbranch_execz .LBB0_1018
	v_add_u32_e32 v2, s27, v53
	v_add_u32_e32 v76, v2, v49
	v_add_u32_e32 v77, v2, v50
	ds_read_b128 v[56:59], v76
	ds_read_b128 v[60:63], v76 offset:2048
	ds_read_b128 v[64:67], v77
	ds_read_b128 v[72:75], v77 offset:4096
	s_waitcnt lgkmcnt(3)
	v_mfma_f32_16x16x32_bf16 v[56:59], v[56:59], v[20:23], 0
	ds_read_b128 v[68:71], v77 offset:2048
	s_add_i32 s36, s0, 0x7f
	v_cmp_ge_u32_e32 vcc, s36, v48
	s_waitcnt lgkmcnt(2)
	v_mfma_f32_16x16x32_bf16 v[56:59], v[64:67], v[24:27], v[56:59]
	ds_read_b128 v[64:67], v76 offset:4096
	v_mfma_f32_16x16x32_bf16 v[60:63], v[60:63], v[20:23], 0
	s_nop 5
	v_exp_f32_e64 v166, -v56
	v_exp_f32_e64 v167, -v57
	v_exp_f32_e64 v168, -v58
	s_waitcnt lgkmcnt(1)
	v_mfma_f32_16x16x32_bf16 v[60:63], v[68:71], v[24:27], v[60:63]
	ds_read_b128 v[68:71], v76 offset:6144
	ds_read_b128 v[76:79], v77 offset:6144
	v_exp_f32_e64 v169, -v59
	s_waitcnt lgkmcnt(2)
	v_mfma_f32_16x16x32_bf16 v[64:67], v[64:67], v[20:23], 0
	s_nop 2
	v_exp_f32_e64 v170, -v60
	v_exp_f32_e64 v171, -v61
	v_exp_f32_e64 v172, -v62
	v_mfma_f32_16x16x32_bf16 v[146:149], v[72:75], v[24:27], v[64:67]
	v_exp_f32_e64 v173, -v63
	s_waitcnt lgkmcnt(1)
	v_mfma_f32_16x16x32_bf16 v[64:67], v[68:71], v[20:23], 0
	s_waitcnt lgkmcnt(0)
	v_mfma_f32_16x16x32_bf16 v[150:153], v[76:79], v[24:27], v[64:67]
	s_nop 2
	v_exp_f32_e64 v174, -v146
	v_exp_f32_e64 v175, -v147
	v_exp_f32_e64 v176, -v148
	v_exp_f32_e64 v177, -v149
	s_nop 0
	v_exp_f32_e64 v178, -v150
	v_exp_f32_e64 v179, -v151
	v_exp_f32_e64 v180, -v152
	v_exp_f32_e64 v181, -v153
	v_pk_add_f32 v[182:183], v[166:167], 1.0 op_sel_hi:[1,0]
	v_pk_add_f32 v[184:185], v[168:169], 1.0 op_sel_hi:[1,0]
	v_pk_add_f32 v[186:187], v[170:171], 1.0 op_sel_hi:[1,0]
	v_pk_add_f32 v[188:189], v[172:173], 1.0 op_sel_hi:[1,0]
	v_pk_add_f32 v[190:191], v[174:175], 1.0 op_sel_hi:[1,0]
	v_pk_add_f32 v[192:193], v[176:177], 1.0 op_sel_hi:[1,0]
	v_pk_add_f32 v[194:195], v[178:179], 1.0 op_sel_hi:[1,0]
	v_pk_add_f32 v[196:197], v[180:181], 1.0 op_sel_hi:[1,0]
	v_rcp_f32_e32 v198, v182
	v_rcp_f32_e32 v199, v183
	v_rcp_f32_e32 v200, v184
	v_rcp_f32_e32 v201, v185
	v_rcp_f32_e32 v202, v186
	v_rcp_f32_e32 v203, v187
	v_rcp_f32_e32 v204, v188
	v_rcp_f32_e32 v205, v189
	v_rcp_f32_e32 v206, v190
	v_rcp_f32_e32 v207, v191
	v_rcp_f32_e32 v208, v192
	v_rcp_f32_e32 v209, v193
	v_rcp_f32_e32 v210, v194
	v_rcp_f32_e32 v211, v195
	v_rcp_f32_e32 v212, v196
	v_rcp_f32_e32 v213, v197
	s_and_saveexec_b64 s[36:37], vcc
	s_cbranch_execz .Lpk_join
	v_cmp_lt_i32_e64 s[66:67], 0, v54
	v_cmp_lt_i32_e64 s[68:69], 1, v54
	v_cmp_lt_i32_e64 s[70:71], 2, v54
	v_cmp_lt_i32_e64 s[72:73], 3, v54
	v_cndmask_b32_e64 v198, 0, v198, s[66:67]
	v_cndmask_b32_e64 v199, 0, v199, s[68:69]
	v_cndmask_b32_e64 v200, 0, v200, s[70:71]
	v_cndmask_b32_e64 v201, 0, v201, s[72:73]
	v_cmp_lt_i32_e64 s[66:67], 4, v54
	v_cmp_lt_i32_e64 s[68:69], 5, v54
	v_cmp_lt_i32_e64 s[70:71], 6, v54
	v_cmp_lt_i32_e64 s[72:73], 7, v54
	v_cndmask_b32_e64 v202, 0, v202, s[66:67]
	v_cndmask_b32_e64 v203, 0, v203, s[68:69]
	v_cndmask_b32_e64 v204, 0, v204, s[70:71]
	v_cndmask_b32_e64 v205, 0, v205, s[72:73]
	v_cmp_lt_i32_e64 s[66:67], 8, v54
	v_cmp_lt_i32_e64 s[68:69], 9, v54
	v_cmp_lt_i32_e64 s[70:71], 10, v54
	v_cmp_lt_i32_e64 s[72:73], 11, v54
	v_cndmask_b32_e64 v206, 0, v206, s[66:67]
	v_cndmask_b32_e64 v207, 0, v207, s[68:69]
	v_cndmask_b32_e64 v208, 0, v208, s[70:71]
	v_cndmask_b32_e64 v209, 0, v209, s[72:73]
	v_cmp_lt_i32_e64 s[66:67], 12, v54
	v_cmp_lt_i32_e64 s[68:69], 13, v54
	v_cmp_lt_i32_e64 s[70:71], 14, v54
	v_cmp_lt_i32_e64 s[72:73], 15, v54
	v_cndmask_b32_e64 v210, 0, v210, s[66:67]
	v_cndmask_b32_e64 v211, 0, v211, s[68:69]
	v_cndmask_b32_e64 v212, 0, v212, s[70:71]
	v_cndmask_b32_e64 v213, 0, v213, s[72:73]
.Lpk_join:
	s_or_b64 exec, exec, s[36:37]
	v_mov_b32_e32 v181, 1.0
	v_sub_f32_e32 v180, 1.0, v213
	v_fma_f32 v179, -v180, v212, v180
	v_fma_f32 v178, -v179, v211, v179
	v_fma_f32 v177, -v178, v210, v178
	v_fma_f32 v176, -v177, v209, v177
	v_fma_f32 v175, -v176, v208, v176
	v_fma_f32 v174, -v175, v207, v175
	v_fma_f32 v173, -v174, v206, v174
	v_fma_f32 v172, -v173, v205, v173
	v_fma_f32 v171, -v172, v204, v172
	v_fma_f32 v170, -v171, v203, v171
	v_fma_f32 v169, -v170, v202, v170
	v_fma_f32 v168, -v169, v201, v169
	v_fma_f32 v167, -v168, v200, v168
	v_fma_f32 v166, -v167, v199, v167
	v_fma_f32 v240, -v166, v198, v166
	s_nop 0
	ds_bpermute_b32 v241, v162, v240
	ds_bpermute_b32 v242, v163, v240
	ds_bpermute_b32 v243, v164, v240
	s_waitcnt lgkmcnt(2)
	v_cndmask_b32_e64 v244, 1.0, v241, s[10:11]
	s_waitcnt lgkmcnt(1)
	v_mul_f32_e32 v245, v244, v242
	v_cndmask_b32_e64 v244, v244, v245, s[4:5]
	s_waitcnt lgkmcnt(0)
	v_mul_f32_e32 v245, v244, v243
	v_cndmask_b32_e64 v244, v244, v245, s[6:7]
	v_mul_f32_e32 v230, v55, v244
	v_mov_b32_e32 v231, v230
	v_pk_mul_f32 v[182:183], v[166:167], v[230:231]
	v_pk_mul_f32 v[184:185], v[168:169], v[230:231]
	v_pk_mul_f32 v[186:187], v[170:171], v[230:231]
	v_pk_mul_f32 v[188:189], v[172:173], v[230:231]
	v_pk_mul_f32 v[190:191], v[174:175], v[230:231]
	v_pk_mul_f32 v[192:193], v[176:177], v[230:231]
	v_pk_mul_f32 v[194:195], v[178:179], v[230:231]
	v_pk_mul_f32 v[196:197], v[180:181], v[230:231]
	v_pk_mul_f32 v[182:183], v[198:199], v[182:183]
	v_pk_mul_f32 v[184:185], v[200:201], v[184:185]
	v_pk_mul_f32 v[186:187], v[202:203], v[186:187]
	v_pk_mul_f32 v[188:189], v[204:205], v[188:189]
	v_pk_mul_f32 v[190:191], v[206:207], v[190:191]
	v_pk_mul_f32 v[192:193], v[208:209], v[192:193]
	v_pk_mul_f32 v[194:195], v[210:211], v[194:195]
	v_pk_mul_f32 v[196:197], v[212:213], v[196:197]
	v_cvt_pk_bf16_f32 v232, v182, v183
	v_cvt_pk_bf16_f32 v233, v184, v185
	v_cvt_pk_bf16_f32 v234, v186, v187
	v_cvt_pk_bf16_f32 v235, v188, v189
	v_cvt_pk_bf16_f32 v236, v190, v191
	v_cvt_pk_bf16_f32 v237, v192, v193
	v_cvt_pk_bf16_f32 v238, v194, v195
	v_cvt_pk_bf16_f32 v239, v196, v197
	v_add_u32_e32 v81, v2, v51
	ds_read_b128 v[60:63], v81 offset:8192
	ds_read_b128 v[72:75], v81 offset:10240
	v_add_u32_e32 v2, v2, v52
	ds_read_b128 v[64:67], v2 offset:8192
	s_waitcnt lgkmcnt(2)
	v_mfma_f32_16x16x32_bf16 v[8:11], v[60:63], v[232:235], v[8:11]
	ds_read_b128 v[60:63], v2 offset:10240
	v_mul_f32_e32 v246, v242, v243
	v_mul_f32_e32 v247, v240, v241
	s_waitcnt lgkmcnt(2)
	v_mfma_f32_16x16x32_bf16 v[12:15], v[72:75], v[232:235], v[12:15]
	s_waitcnt lgkmcnt(1)
	v_mfma_f32_16x16x32_bf16 v[8:11], v[64:67], v[236:239], v[8:11]
	s_waitcnt lgkmcnt(0)
	v_mfma_f32_16x16x32_bf16 v[12:15], v[60:63], v[236:239], v[12:15]
	ds_read_b128 v[60:63], v81 offset:12288
	ds_read_b128 v[64:67], v81 offset:14336
	s_waitcnt lgkmcnt(1)
	v_mfma_f32_16x16x32_bf16 v[16:19], v[60:63], v[232:235], v[16:19]
	ds_read_b128 v[60:63], v2 offset:12288
	ds_read_b128 v[72:75], v2 offset:14336
	s_waitcnt lgkmcnt(2)
	v_mfma_f32_16x16x32_bf16 v[4:7], v[64:67], v[232:235], v[4:7]
	v_mul_f32_e32 v246, v246, v247
	v_mul_f32_e32 v55, v55, v246
	s_waitcnt lgkmcnt(1)
	v_mfma_f32_16x16x32_bf16 v[16:19], v[60:63], v[236:239], v[16:19]
	v_cmp_eq_f32_e32 vcc, 0, v55
	s_cmp_eq_u64 vcc, exec
	s_cselect_b64 s[36:37], -1, 0
	s_waitcnt lgkmcnt(0)
	v_mfma_f32_16x16x32_bf16 v[4:7], v[72:75], v[236:239], v[4:7]
	v_cndmask_b32_e64 v56, 0, 1, s[36:37]
